# LN statistics exchange: dropped the L1 invalidate after the panel-counter poll (the slot loads that follow are sc1 loads of sc1-stored data and bypass L1)
# speedup vs baseline: 1.0095x; 1.0095x over previous
;     __device__ __forceinline__ void run(const f32x4 (&v)[2][2][4][2], const Unit& u, int wr, int wc, int fr, int fq, PG8_LAS unsigned char* lds, int wid, int lane) const {
;     ...
;             __builtin_amdgcn_fence(__ATOMIC_ACQUIRE, "agent");
;         }
;         asm volatile("s_waitcnt vmcnt(0) lgkmcnt(0)" ::: "memory"); __builtin_amdgcn_s_barrier(); asm volatile("" ::: "memory");
;         if (lane < 32) {
;             const unsigned long long* slot = xbuf + (size_t)(u.pm * BM + row) * 8; float mt[8], m2[8]; float ms = 0.f;
; #pragma unroll
;             for (int t = 0; t < 8; ++t) { const unsigned long long w = __hip_atomic_load(slot + t, __ATOMIC_RELAXED, __HIP_MEMORY_SCOPE_AGENT); mt[t] = __uint_as_float((unsigned)w); m2[t] = __uint_as_float((unsigned)(w >> 32)); ms += mt[t]; }
;             const float mean = ms * 0.125f; float q = 0.f;
; #pragma unroll
;             for (int t = 0; t < 8; ++t) { const float dm = mt[t] - mean; q += m2[t] + 256.0f * dm * dm; }
;             S[row] = (f32x2v){mean, 1.0f / sqrtf(q * (1.0f / 2048.0f) + eps)};
.LBB0_466:
.LBB0_467:
	s_waitcnt vmcnt(0) lgkmcnt(0)
	s_barrier
	s_and_saveexec_b64 s[6:7], s[4:5]
	s_cbranch_execz .LBB0_469
	v_lshlrev_b64 v[0:1], 6, v[0:1]
	v_lshl_add_u64 v[0:1], s[8:9], 0, v[0:1]
	global_load_dwordx2 v[4:5], v[0:1], off sc1
	global_load_dwordx2 v[6:7], v[0:1], off offset:8 sc1
	global_load_dwordx2 v[8:9], v[0:1], off offset:16 sc1
	global_load_dwordx2 v[10:11], v[0:1], off offset:24 sc1
	global_load_dwordx2 v[12:13], v[0:1], off offset:32 sc1
	global_load_dwordx2 v[14:15], v[0:1], off offset:40 sc1
	global_load_dwordx2 v[16:17], v[0:1], off offset:48 sc1
	global_load_dwordx2 v[18:19], v[0:1], off offset:56 sc1
	s_mov_b32 s4, 0xf800000
	v_lshl_add_u32 v2, v2, 3, 0
	s_waitcnt vmcnt(7)
	v_add_f32_e32 v3, 0, v4
	s_waitcnt vmcnt(6)
	v_add_f32_e32 v3, v3, v6
	s_waitcnt vmcnt(5)
	v_add_f32_e32 v3, v3, v8
	s_waitcnt vmcnt(4)
	v_add_f32_e32 v3, v3, v10
	s_waitcnt vmcnt(3)
	v_add_f32_e32 v3, v3, v12
	s_waitcnt vmcnt(2)
	v_add_f32_e32 v3, v3, v14
	s_waitcnt vmcnt(1)
	v_add_f32_e32 v3, v3, v16
	s_waitcnt vmcnt(0)
	v_add_f32_e32 v1, v3, v18
	v_fmamk_f32 v3, v1, 0xbe000000, v4
	v_mul_f32_e32 v4, 0x43800000, v3
	v_fmac_f32_e32 v5, v3, v4
	v_fmamk_f32 v4, v1, 0xbe000000, v6
	v_add_f32_e32 v3, 0, v5
	v_mul_f32_e32 v5, 0x43800000, v4
	v_fmac_f32_e32 v7, v4, v5
	v_fmamk_f32 v4, v1, 0xbe000000, v8
	v_mul_f32_e32 v5, 0x43800000, v4
	v_fmac_f32_e32 v9, v4, v5
	v_fmamk_f32 v4, v1, 0xbe000000, v10
	v_mul_f32_e32 v5, 0x43800000, v4
	v_fmac_f32_e32 v11, v4, v5
	v_fmamk_f32 v4, v1, 0xbe000000, v12
	v_mul_f32_e32 v5, 0x43800000, v4
	v_add_f32_e32 v3, v7, v3
	v_fmac_f32_e32 v13, v4, v5
	v_fmamk_f32 v4, v1, 0xbe000000, v14
	v_add_f32_e32 v3, v9, v3
	v_mul_f32_e32 v5, 0x43800000, v4
	v_add_f32_e32 v3, v11, v3
	v_fmac_f32_e32 v15, v4, v5
	v_fmamk_f32 v4, v1, 0xbe000000, v16
	v_mul_f32_e32 v0, 0x3e000000, v1
	v_add_f32_e32 v3, v13, v3
	v_mul_f32_e32 v5, 0x43800000, v4
	v_fmamk_f32 v1, v1, 0xbe000000, v18
	v_add_f32_e32 v3, v15, v3
	v_fmac_f32_e32 v17, v4, v5
	v_mul_f32_e32 v4, 0x43800000, v1
	v_add_f32_e32 v3, v17, v3
	v_fmac_f32_e32 v19, v1, v4
	v_add_f32_e32 v1, v19, v3
	v_mov_b32_e32 v3, 0x3727c5ac
	v_fmamk_f32 v1, v1, 0x3a000000, v3
	v_cmp_gt_f32_e32 vcc, s4, v1
	v_mul_f32_e32 v3, 0x4f800000, v1
	s_nop 0
	v_cndmask_b32_e32 v1, v1, v3, vcc
	v_sqrt_f32_e32 v3, v1
	s_nop 0
	v_add_u32_e32 v4, -1, v3
	v_fma_f32 v5, -v4, v3, v1
	v_cmp_ge_f32_e64 s[4:5], 0, v5
	v_add_u32_e32 v5, 1, v3
	s_nop 0
	v_cndmask_b32_e64 v4, v3, v4, s[4:5]
	v_fma_f32 v3, -v5, v3, v1
	v_cmp_lt_f32_e64 s[4:5], 0, v3
	s_nop 1
	v_cndmask_b32_e64 v3, v4, v5, s[4:5]
	v_mul_f32_e32 v4, 0x37800000, v3
	v_cndmask_b32_e32 v3, v3, v4, vcc
	v_cmp_class_f32_e32 vcc, v1, v233
	s_nop 1
	v_cndmask_b32_e32 v1, v3, v1, vcc
	v_div_scale_f32 v3, s[4:5], v1, v1, 1.0
	v_rcp_f32_e32 v4, v3
	s_nop 0
	v_fma_f32 v5, -v3, v4, 1.0
	v_fmac_f32_e32 v4, v5, v4
	v_div_scale_f32 v5, vcc, 1.0, v1, 1.0
	v_mul_f32_e32 v6, v5, v4
	v_fma_f32 v7, -v3, v6, v5
	v_fmac_f32_e32 v6, v7, v4
	v_fma_f32 v3, -v3, v6, v5
	v_div_fmas_f32 v3, v3, v4, v6
	v_div_fixup_f32 v1, v3, v1, 1.0
	ds_write_b64 v2, v[0:1] offset:8192
